# v13_norm1
# baseline (speedup 1.0000x reference)
; __device__ __forceinline__ void phase_outnorm(const Params& p, int l, LAS unsigned char* lds, int bid, int G, int tid) {
;     ...
;         { const int c = tid;
; #pragma unroll
;             for (int q = 0; q < 8; ++q) { const u32x4 raw = *(const u32x4*)(yht + (size_t)c * T + tb + q * 8);
;                 yt[(q * 8 + 0) * 520 + c] = (u16)(raw.x & 0xffff); yt[(q * 8 + 1) * 520 + c] = (u16)(raw.x >> 16); yt[(q * 8 + 2) * 520 + c] = (u16)(raw.y & 0xffff); yt[(q * 8 + 3) * 520 + c] = (u16)(raw.y >> 16);
;                 yt[(q * 8 + 4) * 520 + c] = (u16)(raw.z & 0xffff); yt[(q * 8 + 5) * 520 + c] = (u16)(raw.z >> 16); yt[(q * 8 + 6) * 520 + c] = (u16)(raw.w & 0xffff); yt[(q * 8 + 7) * 520 + c] = (u16)(raw.w >> 16); } }
;         __syncthreads();
.LBB0_119:
	s_lshl_b32 s0, s8, 6
	s_ashr_i32 s1, s0, 31
	v_lshl_add_u64 v[66:67], s[0:1], 1, v[124:125]
	s_barrier
	global_load_dwordx4 v[220:223], v[66:67], off
	s_mov_b32 s9, 0
	v_mov_b32_e32 v152, v151
	v_mov_b32_e32 v153, v149
	global_load_dwordx4 v[224:227], v[66:67], off offset:16
	global_load_dwordx4 v[228:231], v[66:67], off offset:32
	global_load_dwordx4 v[232:235], v[66:67], off offset:48
	global_load_dwordx4 v[236:239], v[66:67], off offset:64
	global_load_dwordx4 v[240:243], v[66:67], off offset:80
	global_load_dwordx4 v[244:247], v[66:67], off offset:96
	global_load_dwordx4 v[248:251], v[66:67], off offset:112
	s_waitcnt vmcnt(7)
	ds_write_b16 v148, v220
	ds_write_b16_d16_hi v148, v220 offset:1040
	ds_write_b16 v148, v221 offset:2080
	ds_write_b16_d16_hi v148, v221 offset:3120
	ds_write_b16 v148, v222 offset:4160
	ds_write_b16_d16_hi v148, v222 offset:5200
	ds_write_b16 v148, v223 offset:6240
	ds_write_b16_d16_hi v148, v223 offset:7280
	s_waitcnt vmcnt(6)
	ds_write_b16 v148, v224 offset:8320
	ds_write_b16_d16_hi v148, v224 offset:9360
	ds_write_b16 v148, v225 offset:10400
	ds_write_b16_d16_hi v148, v225 offset:11440
	ds_write_b16 v148, v226 offset:12480
	ds_write_b16_d16_hi v148, v226 offset:13520
	ds_write_b16 v148, v227 offset:14560
	ds_write_b16_d16_hi v148, v227 offset:15600
	s_waitcnt vmcnt(5)
	ds_write_b16 v148, v228 offset:16640
	ds_write_b16_d16_hi v148, v228 offset:17680
	ds_write_b16 v148, v229 offset:18720
	ds_write_b16_d16_hi v148, v229 offset:19760
	ds_write_b16 v148, v230 offset:20800
	ds_write_b16_d16_hi v148, v230 offset:21840
	ds_write_b16 v148, v231 offset:22880
	ds_write_b16_d16_hi v148, v231 offset:23920
	s_waitcnt vmcnt(4)
	ds_write_b16 v148, v232 offset:24960
	ds_write_b16_d16_hi v148, v232 offset:26000
	ds_write_b16 v148, v233 offset:27040
	ds_write_b16_d16_hi v148, v233 offset:28080
	ds_write_b16 v148, v234 offset:29120
	ds_write_b16_d16_hi v148, v234 offset:30160
	ds_write_b16 v148, v235 offset:31200
	ds_write_b16_d16_hi v148, v235 offset:32240
	s_waitcnt vmcnt(3)
	ds_write_b16 v148, v236 offset:33280
	ds_write_b16_d16_hi v148, v236 offset:34320
	ds_write_b16 v148, v237 offset:35360
	ds_write_b16_d16_hi v148, v237 offset:36400
	ds_write_b16 v148, v238 offset:37440
	ds_write_b16_d16_hi v148, v238 offset:38480
	ds_write_b16 v148, v239 offset:39520
	ds_write_b16_d16_hi v148, v239 offset:40560
	s_waitcnt vmcnt(2)
	ds_write_b16 v148, v240 offset:41600
	ds_write_b16_d16_hi v148, v240 offset:42640
	ds_write_b16 v148, v241 offset:43680
	ds_write_b16_d16_hi v148, v241 offset:44720
	ds_write_b16 v148, v242 offset:45760
	ds_write_b16_d16_hi v148, v242 offset:46800
	ds_write_b16 v148, v243 offset:47840
	ds_write_b16_d16_hi v148, v243 offset:48880
	s_waitcnt vmcnt(1)
	ds_write_b16 v148, v244 offset:49920
	ds_write_b16_d16_hi v148, v244 offset:50960
	ds_write_b16 v148, v245 offset:52000
	ds_write_b16_d16_hi v148, v245 offset:53040
	ds_write_b16 v148, v246 offset:54080
	ds_write_b16_d16_hi v148, v246 offset:55120
	ds_write_b16 v148, v247 offset:56160
	ds_write_b16_d16_hi v148, v247 offset:57200
	s_waitcnt vmcnt(0)
	ds_write_b16 v148, v248 offset:58240
	ds_write_b16_d16_hi v148, v248 offset:59280
	ds_write_b16 v148, v249 offset:60320
	ds_write_b16_d16_hi v148, v249 offset:61360
	ds_write_b16 v148, v250 offset:62400
	ds_write_b16_d16_hi v148, v250 offset:63440
	ds_write_b16 v148, v251 offset:64480
	ds_write_b16_d16_hi v148, v251 offset:65520
	s_waitcnt lgkmcnt(0)
	s_barrier
	s_branch .LBB0_121

; __device__ __forceinline__ void phase_foldw(const Params& p, int l, LAS unsigned char* lds, int bid, int G, int tid) {
;     ...
;     for (int item = bid; item < 256; item += G) {
;         const int g = item >> 6, cs = (item >> 5) & 1, k0 = (item & 31) * 64;
;         const float* wsrc = wcs + (size_t)((l * 4 + g) * 2 + cs) * 16384;
;         __syncthreads();
.LBB0_387:
	s_ashr_i32 s6, s8, 6
	s_lshl_b32 s0, s6, 1
	s_bfe_u32 s9, s8, 0x10005
	s_add_i32 s0, s0, s3
	s_or_b32 s0, s0, s9
	s_ashr_i32 s1, s0, 31
	s_lshl_b32 s7, s8, 6
	s_lshl_b64 s[0:1], s[0:1], 16
	v_readlane_b32 s10, v253, 27
	v_readlane_b32 s11, v253, 28
	s_add_u32 s0, s10, s0
	s_addc_u32 s1, s11, s1
	v_lshl_add_u64 v[18:19], v[98:99], 2, s[0:1]
	s_barrier
; #define LAS __attribute__((address_space(3)))
; __device__ __forceinline__ void phase_foldw(const Params& p, int l, LAS unsigned char* lds, int bid, int G, int tid) {
;     ...
;         __syncthreads();
; #pragma unroll
;         for (int i = 0; i < 8; ++i) { const int e = (tid + 512 * i) * 4; *(LAS f32x4*)(Wc + e) = *(const f32x4*)(wsrc + e); }
; #pragma unroll
;         for (int i = 0; i < 16; ++i) { const int e = tid + 512 * i, kk = e >> 7, cc = e & 127; slab[kk * 129 + cc] = w_in[(size_t)(k0 + kk) * 5120 + 3072 + g * 128 + cc]; }
;         __syncthreads();
;         { const int kk = tid & 63, dg = tid >> 6; float acc[16];
; #pragma unroll
;             for (int i = 0; i < 16; ++i) acc[i] = 0.f;
	global_load_dwordx4 v[140:143], v[18:19], off
	s_and_b32 s10, s7, 0x7c0
	v_mov_b32_e32 v69, v1
	v_mov_b32_e32 v70, v52
	v_lshl_add_u64 v[18:19], v[4:5], 2, s[0:1]
	global_load_dwordx4 v[144:147], v[18:19], off
	v_lshl_add_u64 v[18:19], v[6:7], 2, s[0:1]
	global_load_dwordx4 v[148:151], v[18:19], off
	v_lshl_add_u64 v[18:19], v[8:9], 2, s[0:1]
	global_load_dwordx4 v[152:155], v[18:19], off
	v_lshl_add_u64 v[18:19], v[10:11], 2, s[0:1]
	global_load_dwordx4 v[156:159], v[18:19], off
	v_lshl_add_u64 v[18:19], v[12:13], 2, s[0:1]
	global_load_dwordx4 v[160:163], v[18:19], off
	v_lshl_add_u64 v[18:19], v[14:15], 2, s[0:1]
	global_load_dwordx4 v[164:167], v[18:19], off
	v_lshl_add_u64 v[18:19], v[16:17], 2, s[0:1]
	global_load_dwordx4 v[168:171], v[18:19], off
	s_lshl_b32 s0, s6, 7
	s_ashr_i32 s1, s0, 31
	v_add_u32_e32 v20, s10, v36
	v_mov_b64_e32 v[18:19], s[4:5]
	v_mad_i64_i32 v[20:21], s[6:7], v20, s53, v[18:19]
	s_lshl_b64 s[6:7], s[0:1], 2
	s_nop 0
	v_lshl_add_u64 v[22:23], v[20:21], 0, s[6:7]
	v_lshlrev_b32_e32 v20, 2, v139
	v_mov_b32_e32 v21, v0
	v_lshl_add_u64 v[22:23], v[22:23], 0, v[20:21]
	s_movk_i32 s1, 0x3000
	v_add_co_u32_e32 v22, vcc, s1, v22
	s_nop 1
	v_addc_co_u32_e32 v23, vcc, 0, v23, vcc
	global_load_dword v172, v[22:23], off
	v_add_u32_e32 v22, s10, v37
	v_mad_i64_i32 v[22:23], s[12:13], v22, s53, v[18:19]
	v_lshl_add_u64 v[22:23], v[22:23], 0, s[6:7]
	v_lshl_add_u64 v[22:23], v[22:23], 0, v[20:21]
	v_add_co_u32_e32 v22, vcc, s1, v22
	s_nop 1
	v_addc_co_u32_e32 v23, vcc, 0, v23, vcc
	global_load_dword v173, v[22:23], off
	v_add_u32_e32 v22, s10, v38
	v_mad_i64_i32 v[22:23], s[12:13], v22, s53, v[18:19]
	v_lshl_add_u64 v[22:23], v[22:23], 0, s[6:7]
	v_lshl_add_u64 v[22:23], v[22:23], 0, v[20:21]
	v_add_co_u32_e32 v22, vcc, s1, v22
	s_nop 1
	v_addc_co_u32_e32 v23, vcc, 0, v23, vcc
	global_load_dword v174, v[22:23], off
	v_add_u32_e32 v22, s10, v39
	v_mad_i64_i32 v[22:23], s[12:13], v22, s53, v[18:19]
	v_lshl_add_u64 v[22:23], v[22:23], 0, s[6:7]
	v_lshl_add_u64 v[22:23], v[22:23], 0, v[20:21]
	v_add_co_u32_e32 v22, vcc, s1, v22
	s_nop 1
	v_addc_co_u32_e32 v23, vcc, 0, v23, vcc
	global_load_dword v175, v[22:23], off
	v_add_u32_e32 v22, s10, v40
	v_mad_i64_i32 v[22:23], s[12:13], v22, s53, v[18:19]
	v_lshl_add_u64 v[22:23], v[22:23], 0, s[6:7]
	v_lshl_add_u64 v[22:23], v[22:23], 0, v[20:21]
	v_add_co_u32_e32 v22, vcc, s1, v22
	s_nop 1
	v_addc_co_u32_e32 v23, vcc, 0, v23, vcc
	global_load_dword v176, v[22:23], off
	v_add_u32_e32 v22, s10, v41
	v_mad_i64_i32 v[22:23], s[12:13], v22, s53, v[18:19]
	v_lshl_add_u64 v[22:23], v[22:23], 0, s[6:7]
	v_lshl_add_u64 v[22:23], v[22:23], 0, v[20:21]
	v_add_co_u32_e32 v22, vcc, s1, v22
	s_nop 1
	v_addc_co_u32_e32 v23, vcc, 0, v23, vcc
	global_load_dword v177, v[22:23], off
	v_add_u32_e32 v22, s10, v42
	v_mad_i64_i32 v[22:23], s[12:13], v22, s53, v[18:19]
	v_lshl_add_u64 v[22:23], v[22:23], 0, s[6:7]
	v_lshl_add_u64 v[22:23], v[22:23], 0, v[20:21]
	v_add_co_u32_e32 v22, vcc, s1, v22
	s_nop 1
	v_addc_co_u32_e32 v23, vcc, 0, v23, vcc
	global_load_dword v196, v[22:23], off
	v_add_u32_e32 v22, s10, v43
	v_mad_i64_i32 v[22:23], s[12:13], v22, s53, v[18:19]
	v_lshl_add_u64 v[22:23], v[22:23], 0, s[6:7]
	v_lshl_add_u64 v[22:23], v[22:23], 0, v[20:21]
	v_add_co_u32_e32 v22, vcc, s1, v22
	s_nop 1
	v_addc_co_u32_e32 v23, vcc, 0, v23, vcc
	global_load_dword v197, v[22:23], off
	v_add_u32_e32 v22, s10, v44
	v_mad_i64_i32 v[22:23], s[12:13], v22, s53, v[18:19]
	v_lshl_add_u64 v[22:23], v[22:23], 0, s[6:7]
	v_lshl_add_u64 v[22:23], v[22:23], 0, v[20:21]
	v_add_co_u32_e32 v22, vcc, s1, v22
	s_nop 1
	v_addc_co_u32_e32 v23, vcc, 0, v23, vcc
	global_load_dword v198, v[22:23], off
	v_add_u32_e32 v22, s10, v45
	v_mad_i64_i32 v[22:23], s[12:13], v22, s53, v[18:19]
	v_lshl_add_u64 v[22:23], v[22:23], 0, s[6:7]
	v_lshl_add_u64 v[22:23], v[22:23], 0, v[20:21]
	v_add_co_u32_e32 v22, vcc, s1, v22
	s_nop 1
	v_addc_co_u32_e32 v23, vcc, 0, v23, vcc
	global_load_dword v199, v[22:23], off
	v_add_u32_e32 v22, s10, v46
	v_mad_i64_i32 v[22:23], s[12:13], v22, s53, v[18:19]
	v_lshl_add_u64 v[22:23], v[22:23], 0, s[6:7]
	v_lshl_add_u64 v[22:23], v[22:23], 0, v[20:21]
	v_add_co_u32_e32 v22, vcc, s1, v22
	s_nop 1
	v_addc_co_u32_e32 v23, vcc, 0, v23, vcc
	global_load_dword v200, v[22:23], off
	v_add_u32_e32 v22, s10, v47
	v_mad_i64_i32 v[22:23], s[12:13], v22, s53, v[18:19]
	v_lshl_add_u64 v[22:23], v[22:23], 0, s[6:7]
	v_lshl_add_u64 v[22:23], v[22:23], 0, v[20:21]
	v_add_co_u32_e32 v22, vcc, s1, v22
	s_nop 1
	v_addc_co_u32_e32 v23, vcc, 0, v23, vcc
	global_load_dword v201, v[22:23], off
	v_add_u32_e32 v22, s10, v48
	v_mad_i64_i32 v[22:23], s[12:13], v22, s53, v[18:19]
	v_lshl_add_u64 v[22:23], v[22:23], 0, s[6:7]
	v_lshl_add_u64 v[22:23], v[22:23], 0, v[20:21]
	v_add_co_u32_e32 v22, vcc, s1, v22
	s_nop 1
	v_addc_co_u32_e32 v23, vcc, 0, v23, vcc
	global_load_dword v202, v[22:23], off
	v_add_u32_e32 v22, s10, v49
	v_mad_i64_i32 v[22:23], s[12:13], v22, s53, v[18:19]
	v_lshl_add_u64 v[22:23], v[22:23], 0, s[6:7]
	v_lshl_add_u64 v[22:23], v[22:23], 0, v[20:21]
	v_add_co_u32_e32 v22, vcc, s1, v22
	s_nop 1
	v_addc_co_u32_e32 v23, vcc, 0, v23, vcc
	global_load_dword v203, v[22:23], off
	v_add_u32_e32 v22, s10, v50
	v_mad_i64_i32 v[22:23], s[12:13], v22, s53, v[18:19]
	v_lshl_add_u64 v[22:23], v[22:23], 0, s[6:7]
	v_lshl_add_u64 v[22:23], v[22:23], 0, v[20:21]
	v_add_co_u32_e32 v22, vcc, s1, v22
	s_movk_i32 s1, 0x80
	s_nop 0
	v_addc_co_u32_e32 v23, vcc, 0, v23, vcc
	global_load_dword v204, v[22:23], off
	v_add_u32_e32 v22, s10, v51
	v_mad_i64_i32 v[18:19], s[12:13], v22, s53, v[18:19]
	v_lshl_add_u64 v[18:19], v[18:19], 0, s[6:7]
	v_lshl_add_u64 v[18:19], v[18:19], 0, v[20:21]
	v_add_co_u32_e32 v18, vcc, 0x3000, v18
	s_nop 1
	v_addc_co_u32_e32 v19, vcc, 0, v19, vcc
	global_load_dword v205, v[18:19], off
	s_waitcnt vmcnt(16)
	ds_write_b128 v35, v[140:143] offset:1024
	ds_write_b128 v35, v[144:147] offset:9216
	ds_write_b128 v35, v[148:151] offset:17408
	ds_write_b128 v35, v[152:155] offset:25600
	ds_write_b128 v35, v[156:159] offset:33792
	ds_write_b128 v35, v[160:163] offset:41984
	ds_write_b128 v35, v[164:167] offset:50176
	ds_write_b128 v35, v[168:171] offset:58368
	s_waitcnt vmcnt(0)
	ds_write_b32 v53, v172
	ds_write_b32 v54, v173
	ds_write_b32 v55, v174
	ds_write_b32 v56, v175
	ds_write_b32 v57, v176
	ds_write_b32 v58, v177
	ds_write_b32 v59, v196
	ds_write_b32 v60, v197
	ds_write_b32 v61, v198
	ds_write_b32 v62, v199
	ds_write_b32 v63, v200
	ds_write_b32 v64, v201
	ds_write_b32 v65, v202
	ds_write_b32 v66, v203
	ds_write_b32 v67, v204
	ds_write_b32 v68, v205
	v_mov_b32_e32 v18, 0
	v_mov_b32_e32 v19, v18
	v_mov_b32_e32 v32, v18
	v_mov_b32_e32 v33, v18
	v_mov_b32_e32 v30, v18
	v_mov_b32_e32 v31, v18
	v_mov_b32_e32 v28, v18
	v_mov_b32_e32 v29, v18
	v_mov_b32_e32 v26, v18
	v_mov_b32_e32 v27, v18
	v_mov_b32_e32 v24, v18
	v_mov_b32_e32 v25, v18
	v_mov_b32_e32 v22, v18
	v_mov_b32_e32 v23, v18
	v_mov_b32_e32 v20, v18
	v_mov_b32_e32 v21, v18
	s_waitcnt lgkmcnt(0)
	s_barrier

; __device__ __forceinline__ void phase_norm(const Params& p, int l, int which, int bid, int G, int tid) {
;     ...
;     for (int row = wid * G + bid; row < T; row += 2 * G * 8) {
;         const int row2 = row + G * 8;
;         const float* xr = (l == 0 && which == 0) ? (row < TP ? p.in[0] + (size_t)row * D : p.in[1] + (size_t)(row - TP) * D) : p.out + (size_t)row * D;
;         const float* xr2 = (l == 0 && which == 0) ? (row2 < TP ? p.in[0] + (size_t)row2 * D : p.in[1] + (size_t)(row2 - TP) * D) : p.out + (size_t)row2 * D;
;         f32x4 v[8], v2[8]; float ss = 0.f, ss2 = 0.f;
; #pragma unroll
;         for (int i = 0; i < 8; ++i) { v[i] = *(const f32x4*)(xr + i * 256 + lane * 4); v2[i] = *(const f32x4*)(xr2 + i * 256 + lane * 4); }
; #pragma unroll
;         for (int i = 0; i < 8; ++i) { ss += v[i][0] * v[i][0] + v[i][1] * v[i][1] + v[i][2] * v[i][2] + v[i][3] * v[i][3]; ss2 += v2[i][0] * v2[i][0] + v2[i][1] * v2[i][1] + v2[i][2] * v2[i][2] + v2[i][3] * v2[i][3]; }
;         ss = wave_sum(ss); ss2 = wave_sum(ss2);
.LBB0_394:
	v_mov_b32_e32 v111, v0
	v_lshlrev_b64 v[34:35], 13, v[34:35]
	v_lshl_add_u64 v[38:39], v[38:39], 0, v[110:111]
	v_lshl_add_u64 v[34:35], v[36:37], 0, v[34:35]
	global_load_dwordx4 v[90:93], v[38:39], off
	global_load_dwordx4 v[82:85], v[38:39], off offset:1024
	v_lshl_add_u64 v[34:35], v[34:35], 0, v[110:111]
	global_load_dwordx4 v[94:97], v[34:35], off
	global_load_dwordx4 v[70:73], v[38:39], off offset:2048
	global_load_dwordx4 v[86:89], v[34:35], off offset:1024
	global_load_dwordx4 v[78:81], v[34:35], off offset:2048
	v_add_co_u32_e32 v36, vcc, 0x1000, v34
	v_add_u32_e32 v115, 0xffffc000, v106
	s_nop 0
	v_addc_co_u32_e32 v37, vcc, 0, v35, vcc
	global_load_dwordx4 v[62:65], v[36:37], off
	global_load_dwordx4 v[54:57], v[36:37], off offset:1024
	v_add_co_u32_e32 v128, vcc, 0x1000, v38
	v_lshrrev_b32_e32 v115, 12, v115
	s_nop 0
	v_addc_co_u32_e32 v129, vcc, 0, v39, vcc
	global_load_dwordx4 v[58:61], v[128:129], off
	global_load_dwordx4 v[50:53], v[128:129], off offset:1024
	global_load_dwordx4 v[66:69], v[38:39], off offset:3072
	global_load_dwordx4 v[74:77], v[34:35], off offset:3072
	global_load_dwordx4 v[46:49], v[36:37], off offset:2048
	s_nop 0
	global_load_dwordx4 v[38:41], v[36:37], off offset:3072
	global_load_dwordx4 v[42:45], v[128:129], off offset:2048
	s_nop 0
	global_load_dwordx4 v[34:37], v[128:129], off offset:3072
	v_ashrrev_i32_e32 v113, 13, v100
	v_add_u32_e32 v115, 2, v115
	v_cmp_gt_i32_e32 vcc, s2, v100
	v_readlane_b32 s12, v253, 3
	v_readlane_b32 s13, v253, 4
	v_cndmask_b32_e32 v100, v115, v113, vcc
	v_add_u32_e32 v100, s3, v100
	s_mov_b64 s[18:19], 0x2000
	v_mov_b32_e32 v115, v0
	v_mov_b32_e32 v117, v0
	v_mov_b32_e32 v119, v0
	v_mov_b32_e32 v121, v0
	v_mov_b32_e32 v123, v0
	v_mov_b32_e32 v125, v0
	s_add_i32 s14, s14, s6
	v_lshl_add_u64 v[106:107], v[106:107], 0, s[6:7]
	s_waitcnt vmcnt(13)
	v_mov_b32_e32 v131, v95
	v_mov_b32_e32 v146, v83
	s_waitcnt vmcnt(11)
	v_mov_b32_e32 v147, v87
	v_mov_b32_e32 v130, v91
	v_mov_b32_e32 v136, v82
	v_mov_b32_e32 v137, v86
	v_pk_mul_f32 v[146:147], v[146:147], v[146:147]
	v_mov_b32_e32 v128, v90
	v_mov_b32_e32 v129, v94
	v_pk_mul_f32 v[130:131], v[130:131], v[130:131]
	v_pk_fma_f32 v[136:137], v[136:137], v[136:137], v[146:147]
	v_mov_b32_e32 v146, v71
	s_waitcnt vmcnt(10)
	v_mov_b32_e32 v147, v79
	v_pk_fma_f32 v[128:129], v[128:129], v[128:129], v[130:131]
	v_mov_b32_e32 v130, v70
	v_mov_b32_e32 v131, v78
	v_pk_mul_f32 v[146:147], v[146:147], v[146:147]
	v_mov_b32_e32 v132, v92
	v_pk_fma_f32 v[130:131], v[130:131], v[130:131], v[146:147]
	v_mov_b32_e32 v146, v72
	v_mov_b32_e32 v147, v80
	v_mov_b32_e32 v148, v84
	v_mov_b32_e32 v133, v96
	v_mov_b32_e32 v149, v88
	v_pk_fma_f32 v[130:131], v[146:147], v[146:147], v[130:131]
	s_waitcnt vmcnt(9)
	v_mov_b32_e32 v146, v63
	s_waitcnt vmcnt(8)
	v_mov_b32_e32 v147, v55
	v_mov_b32_e32 v134, v93
	v_mov_b32_e32 v150, v85
	v_pk_fma_f32 v[128:129], v[132:133], v[132:133], v[128:129]
	v_mov_b32_e32 v135, v97
	v_mov_b32_e32 v151, v89
	v_pk_fma_f32 v[136:137], v[148:149], v[148:149], v[136:137]
	v_mov_b32_e32 v148, v62
	v_mov_b32_e32 v149, v54
	v_pk_mul_f32 v[146:147], v[146:147], v[146:147]
	v_mov_b32_e32 v132, v73
	v_mov_b32_e32 v133, v81
	v_pk_fma_f32 v[146:147], v[148:149], v[148:149], v[146:147]
	v_mov_b32_e32 v148, v64
	v_mov_b32_e32 v149, v56
	v_pk_fma_f32 v[128:129], v[134:135], v[134:135], v[128:129]
	v_pk_fma_f32 v[136:137], v[150:151], v[150:151], v[136:137]
	v_pk_fma_f32 v[146:147], v[148:149], v[148:149], v[146:147]
	s_waitcnt vmcnt(7)
	v_mov_b32_e32 v148, v59
	s_waitcnt vmcnt(6)
	v_mov_b32_e32 v149, v51
	v_pk_add_f32 v[128:129], v[128:129], v[136:137]
	v_pk_fma_f32 v[130:131], v[132:133], v[132:133], v[130:131]
	s_waitcnt vmcnt(5)
	v_mov_b32_e32 v132, v67
	s_waitcnt vmcnt(4)
	v_mov_b32_e32 v133, v75
	v_mov_b32_e32 v150, v58
	v_mov_b32_e32 v151, v50
	v_pk_mul_f32 v[148:149], v[148:149], v[148:149]
	v_pk_add_f32 v[128:129], v[128:129], v[130:131]
	v_mov_b32_e32 v130, v66
	v_mov_b32_e32 v131, v74
	v_pk_mul_f32 v[132:133], v[132:133], v[132:133]
	v_mov_b32_e32 v134, v65
	v_mov_b32_e32 v135, v57
	v_pk_fma_f32 v[148:149], v[150:151], v[150:151], v[148:149]
	v_mov_b32_e32 v150, v60
	v_mov_b32_e32 v151, v52
	v_pk_fma_f32 v[130:131], v[130:131], v[130:131], v[132:133]
	v_mov_b32_e32 v132, v68
	v_mov_b32_e32 v133, v76
	v_mov_b32_e32 v136, v61
	v_mov_b32_e32 v137, v53
	v_pk_fma_f32 v[134:135], v[134:135], v[134:135], v[146:147]
	v_pk_fma_f32 v[146:147], v[150:151], v[150:151], v[148:149]
	v_pk_fma_f32 v[130:131], v[132:133], v[132:133], v[130:131]
	v_mov_b32_e32 v132, v69
	v_mov_b32_e32 v133, v77
	v_pk_fma_f32 v[136:137], v[136:137], v[136:137], v[146:147]
	v_pk_fma_f32 v[130:131], v[132:133], v[132:133], v[130:131]
	v_mov_b64_e32 v[132:133], s[12:13]
	v_pk_add_f32 v[128:129], v[128:129], v[130:131]
	v_mov_b32_e32 v130, v136
	v_mov_b32_e32 v131, v134
	v_pk_add_f32 v[150:151], v[128:129], v[130:131]
	s_waitcnt vmcnt(3)
	v_mov_b32_e32 v130, v47
	s_waitcnt vmcnt(2)
	v_mov_b32_e32 v131, v39
	v_mov_b32_e32 v128, v46
	v_mov_b32_e32 v129, v38
	v_pk_mul_f32 v[130:131], v[130:131], v[130:131]
	v_mov_b32_e32 v134, v137
	v_pk_fma_f32 v[128:129], v[128:129], v[128:129], v[130:131]
	v_mov_b32_e32 v130, v48
	v_mov_b32_e32 v131, v40
	v_pk_fma_f32 v[128:129], v[130:131], v[130:131], v[128:129]
	v_mov_b32_e32 v130, v49
	v_mov_b32_e32 v131, v41
	v_pk_fma_f32 v[152:153], v[130:131], v[130:131], v[128:129]
	s_waitcnt vmcnt(1)
	v_mov_b32_e32 v130, v43
	s_waitcnt vmcnt(0)
; __device__ __forceinline__ unsigned pk2(float lo, float hi) { unsigned r; asm("v_cvt_pk_bf16_f32 %0, %1, %2" : "=v"(r) : "v"(lo), "v"(hi)); return r; }
; __device__ __forceinline__ void phase_norm(const Params& p, int l, int which, int bid, int G, int tid) {
;     ...
;         ss = wave_sum(ss); ss2 = wave_sum(ss2);
;         const float rs = rsqrtf(ss * (1.f / 2048.f) + 1e-6f), rs2 = rsqrtf(ss2 * (1.f / 2048.f) + 1e-6f);
;         const float* mb = mod + (size_t)(l * 6 + tok_batch(row)) * 12288 + which * 3 * 2048;
;         const float* mb2 = mod + (size_t)(l * 6 + tok_batch(row2)) * 12288 + which * 3 * 2048;
; #pragma unroll
;         for (int i = 0; i < 8; ++i) { const int col = i * 256 + lane * 4; const f32x4 g4 = gnr[i];
;             { const f32x4 sh = *(const f32x4*)(mb + col), sc = *(const f32x4*)(mb + 2048 + col);
;                 const f32x4 o = v[i] * rs * g4 * (sc + 1.f) + sh; u32x2 w; w.x = pk2(o[0], o[1]); w.y = pk2(o[2], o[3]); *(u32x2*)(act + (size_t)row * D + col) = w; }
;             { const f32x4 sh = *(const f32x4*)(mb2 + col), sc = *(const f32x4*)(mb2 + 2048 + col);
;                 const f32x4 o = v2[i] * rs2 * g4 * (sc + 1.f) + sh; u32x2 w; w.x = pk2(o[0], o[1]); w.y = pk2(o[2], o[3]); *(u32x2*)(act + (size_t)row2 * D + col) = w; } }
	v_mov_b32_e32 v131, v35
	v_mov_b32_e32 v128, v42
	v_mov_b32_e32 v129, v34
	v_pk_mul_f32 v[130:131], v[130:131], v[130:131]
	v_pk_add_f32 v[134:135], v[150:151], v[134:135]
	v_pk_fma_f32 v[128:129], v[128:129], v[128:129], v[130:131]
	v_mov_b32_e32 v130, v44
	v_mov_b32_e32 v131, v36
	v_pk_fma_f32 v[128:129], v[130:131], v[130:131], v[128:129]
	v_mov_b32_e32 v130, v45
	v_mov_b32_e32 v131, v37
	v_pk_fma_f32 v[154:155], v[130:131], v[130:131], v[128:129]
	v_mad_i64_i32 v[128:129], s[12:13], v100, s33, v[132:133]
	v_lshl_add_u64 v[130:131], v[128:129], 0, s[18:19]
	v_lshl_add_u64 v[136:137], v[130:131], 0, v[110:111]
	global_load_dwordx4 v[146:149], v[136:137], off
	v_mov_b32_e32 v136, v154
	v_mov_b32_e32 v137, v152
	v_pk_add_f32 v[134:135], v[134:135], v[136:137]
	v_mov_b32_e32 v152, v155
	v_pk_add_f32 v[134:135], v[134:135], v[152:153]
	ds_bpermute_b32 v137, v1, v135
	ds_bpermute_b32 v136, v1, v134
	s_mov_b32 s12, 0x3a000000
	s_waitcnt lgkmcnt(0)
	v_pk_add_f32 v[134:135], v[134:135], v[136:137]
	ds_bpermute_b32 v137, v140, v135
	ds_bpermute_b32 v136, v140, v134
	s_waitcnt lgkmcnt(0)
	v_pk_add_f32 v[134:135], v[134:135], v[136:137]
	ds_bpermute_b32 v137, v141, v135
	ds_bpermute_b32 v136, v141, v134
	s_waitcnt lgkmcnt(0)
	v_pk_add_f32 v[134:135], v[134:135], v[136:137]
	ds_bpermute_b32 v137, v142, v135
	ds_bpermute_b32 v136, v142, v134
	s_waitcnt lgkmcnt(0)
	v_pk_add_f32 v[134:135], v[134:135], v[136:137]
	ds_bpermute_b32 v137, v143, v135
	ds_bpermute_b32 v136, v143, v134
	s_waitcnt lgkmcnt(0)
	v_pk_add_f32 v[134:135], v[134:135], v[136:137]
	ds_bpermute_b32 v137, v144, v135
	ds_bpermute_b32 v136, v144, v134
	s_waitcnt lgkmcnt(0)
	v_pk_add_f32 v[134:135], v[134:135], v[136:137]
	s_nop 0
	v_pk_fma_f32 v[136:137], v[134:135], s[12:13], v[178:179] op_sel_hi:[1,0,0]
	v_lshl_add_u64 v[134:135], v[128:129], 0, v[110:111]
	v_mul_f32_e32 v100, 0x4b800000, v137
	v_cmp_gt_f32_e32 vcc, s55, v137
	s_waitcnt vmcnt(0)
	v_pk_add_f32 v[152:153], v[146:147], 1.0 op_sel_hi:[1,0]
	v_cndmask_b32_e32 v100, v137, v100, vcc
	v_rsq_f32_e32 v100, v100
	s_nop 0
	v_mul_f32_e32 v113, 0x45800000, v100
	v_cndmask_b32_e32 v100, v100, v113, vcc
	v_pk_mul_f32 v[96:97], v[96:97], v[100:101] op_sel_hi:[1,0]
	v_pk_mul_f32 v[150:151], v[94:95], v[100:101] op_sel_hi:[1,0]
	v_pk_mul_f32 v[94:95], v[4:5], v[96:97]
	v_pk_add_f32 v[96:97], v[148:149], 1.0 op_sel_hi:[1,0]
	global_load_dwordx4 v[146:149], v[134:135], off
	v_cmp_gt_i32_e32 vcc, s2, v126
	v_mov_b32_e32 v113, v0
	v_pk_mul_f32 v[86:87], v[86:87], v[100:101] op_sel_hi:[1,0]
	v_pk_mul_f32 v[88:89], v[88:89], v[100:101] op_sel_hi:[1,0]
	v_pk_mul_f32 v[86:87], v[6:7], v[86:87]
	v_pk_mul_f32 v[88:89], v[8:9], v[88:89]
	v_pk_mul_f32 v[78:79], v[78:79], v[100:101] op_sel_hi:[1,0]
	v_pk_mul_f32 v[80:81], v[80:81], v[100:101] op_sel_hi:[1,0]
	v_pk_mul_f32 v[78:79], v[10:11], v[78:79]
	v_pk_mul_f32 v[80:81], v[12:13], v[80:81]
	v_pk_mul_f32 v[74:75], v[74:75], v[100:101] op_sel_hi:[1,0]
	v_pk_mul_f32 v[76:77], v[76:77], v[100:101] op_sel_hi:[1,0]
	v_pk_mul_f32 v[74:75], v[14:15], v[74:75]
	v_pk_mul_f32 v[76:77], v[16:17], v[76:77]
	v_pk_mul_f32 v[62:63], v[62:63], v[100:101] op_sel_hi:[1,0]
	v_pk_mul_f32 v[64:65], v[64:65], v[100:101] op_sel_hi:[1,0]
	v_pk_mul_f32 v[62:63], v[18:19], v[62:63]
	v_pk_mul_f32 v[64:65], v[20:21], v[64:65]
	v_pk_mul_f32 v[54:55], v[54:55], v[100:101] op_sel_hi:[1,0]
	v_pk_mul_f32 v[56:57], v[56:57], v[100:101] op_sel_hi:[1,0]
	v_pk_mul_f32 v[54:55], v[22:23], v[54:55]
	v_pk_mul_f32 v[56:57], v[24:25], v[56:57]
	v_pk_mul_f32 v[46:47], v[46:47], v[100:101] op_sel_hi:[1,0]
	v_pk_mul_f32 v[48:49], v[48:49], v[100:101] op_sel_hi:[1,0]
	v_pk_mul_f32 v[46:47], v[26:27], v[46:47]
	v_pk_mul_f32 v[48:49], v[28:29], v[48:49]
	v_pk_mul_f32 v[38:39], v[38:39], v[100:101] op_sel_hi:[1,0]
	v_pk_mul_f32 v[40:41], v[40:41], v[100:101] op_sel_hi:[1,0]
	v_pk_mul_f32 v[38:39], v[30:31], v[38:39]
	v_pk_mul_f32 v[40:41], v[32:33], v[40:41]
	s_waitcnt vmcnt(0)
	v_pk_fma_f32 v[96:97], v[96:97], v[94:95], v[148:149]
	v_add_u32_e32 v94, 0xffffc000, v126
	v_lshrrev_b32_e32 v94, 12, v94
	v_add_u32_e32 v94, 2, v94
	v_ashrrev_i32_e32 v95, 13, v126
	v_cndmask_b32_e32 v94, v94, v95, vcc
	v_add_u32_e32 v94, s3, v94
	v_mad_i64_i32 v[94:95], s[12:13], v94, s33, v[132:133]
	v_pk_mul_f32 v[132:133], v[2:3], v[150:151]
	v_cmp_gt_f32_e32 vcc, s55, v136
	v_pk_fma_f32 v[146:147], v[152:153], v[132:133], v[146:147]
	v_lshl_add_u64 v[132:133], v[94:95], 0, s[18:19]
	v_cvt_pk_bf16_f32 v146, v146, v147
	v_cvt_pk_bf16_f32 v147, v96, v97
	global_store_dwordx2 v[108:109], v[146:147], off offset:-2048
	v_lshl_add_u64 v[96:97], v[132:133], 0, v[110:111]
	global_load_dwordx4 v[146:149], v[96:97], off
	v_mul_f32_e32 v96, 0x4b800000, v136
	v_cndmask_b32_e32 v96, v136, v96, vcc
	v_rsq_f32_e32 v96, v96
	v_lshl_add_u64 v[136:137], v[94:95], 0, v[110:111]
	v_mul_f32_e32 v97, 0x45800000, v96
	v_cndmask_b32_e32 v96, v96, v97, vcc
	v_pk_mul_f32 v[92:93], v[92:93], v[96:97] op_sel_hi:[1,0]
	v_pk_mul_f32 v[150:151], v[90:91], v[96:97] op_sel_hi:[1,0]
	v_pk_mul_f32 v[90:91], v[4:5], v[92:93]
	v_pk_mul_f32 v[82:83], v[82:83], v[96:97] op_sel_hi:[1,0]
	v_pk_mul_f32 v[84:85], v[84:85], v[96:97] op_sel_hi:[1,0]
	v_pk_mul_f32 v[82:83], v[6:7], v[82:83]
	v_pk_mul_f32 v[84:85], v[8:9], v[84:85]
	v_pk_mul_f32 v[70:71], v[70:71], v[96:97] op_sel_hi:[1,0]
	v_pk_mul_f32 v[72:73], v[72:73], v[96:97] op_sel_hi:[1,0]
	v_pk_mul_f32 v[70:71], v[10:11], v[70:71]
	v_pk_mul_f32 v[72:73], v[12:13], v[72:73]
	v_pk_mul_f32 v[66:67], v[66:67], v[96:97] op_sel_hi:[1,0]
	v_pk_mul_f32 v[68:69], v[68:69], v[96:97] op_sel_hi:[1,0]
	v_pk_mul_f32 v[66:67], v[14:15], v[66:67]
	v_pk_mul_f32 v[68:69], v[16:17], v[68:69]
	v_pk_mul_f32 v[58:59], v[58:59], v[96:97] op_sel_hi:[1,0]
	v_pk_mul_f32 v[60:61], v[60:61], v[96:97] op_sel_hi:[1,0]
	v_pk_mul_f32 v[58:59], v[18:19], v[58:59]
	v_pk_mul_f32 v[60:61], v[20:21], v[60:61]
	v_pk_mul_f32 v[50:51], v[50:51], v[96:97] op_sel_hi:[1,0]
	v_pk_mul_f32 v[52:53], v[52:53], v[96:97] op_sel_hi:[1,0]
	v_pk_mul_f32 v[50:51], v[22:23], v[50:51]
	v_pk_mul_f32 v[52:53], v[24:25], v[52:53]
	v_pk_mul_f32 v[42:43], v[42:43], v[96:97] op_sel_hi:[1,0]
	v_pk_mul_f32 v[44:45], v[44:45], v[96:97] op_sel_hi:[1,0]
	v_pk_mul_f32 v[42:43], v[26:27], v[42:43]
	v_pk_mul_f32 v[44:45], v[28:29], v[44:45]
	v_pk_mul_f32 v[34:35], v[34:35], v[96:97] op_sel_hi:[1,0]
	v_pk_mul_f32 v[36:37], v[36:37], v[96:97] op_sel_hi:[1,0]
	v_pk_mul_f32 v[34:35], v[30:31], v[34:35]
	v_pk_mul_f32 v[36:37], v[32:33], v[36:37]
	s_waitcnt vmcnt(0)
; __device__ __forceinline__ unsigned pk2(float lo, float hi) { unsigned r; asm("v_cvt_pk_bf16_f32 %0, %1, %2" : "=v"(r) : "v"(lo), "v"(hi)); return r; }
; __device__ __forceinline__ void phase_norm(const Params& p, int l, int which, int bid, int G, int tid) {
;     ...
;         for (int i = 0; i < 8; ++i) { const int col = i * 256 + lane * 4; const f32x4 g4 = gnr[i];
;             { const f32x4 sh = *(const f32x4*)(mb + col), sc = *(const f32x4*)(mb + 2048 + col);
;                 const f32x4 o = v[i] * rs * g4 * (sc + 1.f) + sh; u32x2 w; w.x = pk2(o[0], o[1]); w.y = pk2(o[2], o[3]); *(u32x2*)(act + (size_t)row * D + col) = w; }
;             { const f32x4 sh = *(const f32x4*)(mb2 + col), sc = *(const f32x4*)(mb2 + 2048 + col);
;                 const f32x4 o = v2[i] * rs2 * g4 * (sc + 1.f) + sh; u32x2 w; w.x = pk2(o[0], o[1]); w.y = pk2(o[2], o[3]); *(u32x2*)(act + (size_t)row2 * D + col) = w; } }
	v_pk_add_f32 v[92:93], v[148:149], 1.0 op_sel_hi:[1,0]
	v_pk_add_f32 v[152:153], v[146:147], 1.0 op_sel_hi:[1,0]
	global_load_dwordx4 v[146:149], v[136:137], off
	s_waitcnt vmcnt(0)
	v_pk_fma_f32 v[92:93], v[92:93], v[90:91], v[148:149]
	v_lshlrev_b64 v[90:91], 12, v[126:127]
	v_pk_mul_f32 v[126:127], v[2:3], v[150:151]
	v_lshl_add_u64 v[90:91], v[104:105], 0, v[90:91]
	v_pk_fma_f32 v[126:127], v[152:153], v[126:127], v[146:147]
	v_lshl_add_u64 v[146:147], v[130:131], 0, v[112:113]
	v_cvt_pk_bf16_f32 v126, v126, v127
	v_cvt_pk_bf16_f32 v127, v92, v93
	global_store_dwordx2 v[90:91], v[126:127], off
	v_lshl_add_u64 v[156:157], v[130:131], 0, v[112:113]
	v_lshl_add_u64 v[160:161], v[128:129], 0, v[112:113]
	global_load_dwordx4 v[156:159], v[156:157], off
	global_load_dwordx4 v[160:163], v[160:161], off
	v_lshl_add_u64 v[164:165], v[132:133], 0, v[112:113]
	v_lshl_add_u64 v[168:169], v[94:95], 0, v[112:113]
	global_load_dwordx4 v[164:167], v[164:165], off
	global_load_dwordx4 v[168:171], v[168:169], off
	v_lshl_add_u64 v[172:173], v[130:131], 0, v[114:115]
	v_lshl_add_u64 v[196:197], v[128:129], 0, v[114:115]
	global_load_dwordx4 v[172:175], v[172:173], off
	global_load_dwordx4 v[196:199], v[196:197], off
	v_lshl_add_u64 v[200:201], v[132:133], 0, v[114:115]
	v_lshl_add_u64 v[204:205], v[94:95], 0, v[114:115]
	global_load_dwordx4 v[200:203], v[200:201], off
	global_load_dwordx4 v[204:207], v[204:205], off
	v_lshl_add_u64 v[208:209], v[130:131], 0, v[116:117]
	v_lshl_add_u64 v[220:221], v[128:129], 0, v[116:117]
	global_load_dwordx4 v[208:211], v[208:209], off
	global_load_dwordx4 v[220:223], v[220:221], off
	v_lshl_add_u64 v[224:225], v[132:133], 0, v[116:117]
	v_lshl_add_u64 v[228:229], v[94:95], 0, v[116:117]
	global_load_dwordx4 v[224:227], v[224:225], off
	global_load_dwordx4 v[228:231], v[228:229], off
	v_lshl_add_u64 v[232:233], v[130:131], 0, v[118:119]
	v_lshl_add_u64 v[236:237], v[128:129], 0, v[118:119]
	global_load_dwordx4 v[232:235], v[232:233], off
	global_load_dwordx4 v[236:239], v[236:237], off
	v_lshl_add_u64 v[240:241], v[132:133], 0, v[118:119]
	v_lshl_add_u64 v[244:245], v[94:95], 0, v[118:119]
	global_load_dwordx4 v[240:243], v[240:241], off
	global_load_dwordx4 v[244:247], v[244:245], off
	s_waitcnt vmcnt(14)
	v_pk_add_f32 v[156:157], v[156:157], 1.0 op_sel_hi:[1,0]
	v_pk_add_f32 v[158:159], v[158:159], 1.0 op_sel_hi:[1,0]
	v_pk_fma_f32 v[86:87], v[86:87], v[156:157], v[160:161]
	v_pk_fma_f32 v[88:89], v[88:89], v[158:159], v[162:163]
	v_cvt_pk_bf16_f32 v86, v86, v87
	v_cvt_pk_bf16_f32 v87, v88, v89
	global_store_dwordx2 v[108:109], v[86:87], off offset:-1536
	v_lshl_add_u64 v[156:157], v[130:131], 0, v[120:121]
	v_lshl_add_u64 v[160:161], v[128:129], 0, v[120:121]
	global_load_dwordx4 v[156:159], v[156:157], off
	global_load_dwordx4 v[160:163], v[160:161], off
	s_waitcnt vmcnt(15)
	v_pk_add_f32 v[164:165], v[164:165], 1.0 op_sel_hi:[1,0]
	v_pk_add_f32 v[166:167], v[166:167], 1.0 op_sel_hi:[1,0]
	v_pk_fma_f32 v[82:83], v[82:83], v[164:165], v[168:169]
	v_pk_fma_f32 v[84:85], v[84:85], v[166:167], v[170:171]
	v_cvt_pk_bf16_f32 v82, v82, v83
	v_cvt_pk_bf16_f32 v83, v84, v85
	global_store_dwordx2 v[90:91], v[82:83], off offset:512
	v_lshl_add_u64 v[164:165], v[132:133], 0, v[120:121]
	v_lshl_add_u64 v[168:169], v[94:95], 0, v[120:121]
	global_load_dwordx4 v[164:167], v[164:165], off
	global_load_dwordx4 v[168:171], v[168:169], off
	s_waitcnt vmcnt(16)
	v_pk_add_f32 v[172:173], v[172:173], 1.0 op_sel_hi:[1,0]
	v_pk_add_f32 v[174:175], v[174:175], 1.0 op_sel_hi:[1,0]
	v_pk_fma_f32 v[78:79], v[78:79], v[172:173], v[196:197]
	v_pk_fma_f32 v[80:81], v[80:81], v[174:175], v[198:199]
	v_cvt_pk_bf16_f32 v78, v78, v79
	v_cvt_pk_bf16_f32 v79, v80, v81
	global_store_dwordx2 v[108:109], v[78:79], off offset:-1024
	v_lshl_add_u64 v[172:173], v[130:131], 0, v[122:123]
	v_lshl_add_u64 v[196:197], v[128:129], 0, v[122:123]
	global_load_dwordx4 v[172:175], v[172:173], off
	global_load_dwordx4 v[196:199], v[196:197], off
	s_waitcnt vmcnt(17)
	v_pk_add_f32 v[200:201], v[200:201], 1.0 op_sel_hi:[1,0]
	v_pk_add_f32 v[202:203], v[202:203], 1.0 op_sel_hi:[1,0]
	v_pk_fma_f32 v[70:71], v[70:71], v[200:201], v[204:205]
	v_pk_fma_f32 v[72:73], v[72:73], v[202:203], v[206:207]
	v_cvt_pk_bf16_f32 v70, v70, v71
	v_cvt_pk_bf16_f32 v71, v72, v73
	global_store_dwordx2 v[90:91], v[70:71], off offset:1024
	v_lshl_add_u64 v[200:201], v[132:133], 0, v[122:123]
	v_lshl_add_u64 v[204:205], v[94:95], 0, v[122:123]
	global_load_dwordx4 v[200:203], v[200:201], off
	global_load_dwordx4 v[204:207], v[204:205], off
	s_waitcnt vmcnt(18)
; __device__ __forceinline__ unsigned pk2(float lo, float hi) { unsigned r; asm("v_cvt_pk_bf16_f32 %0, %1, %2" : "=v"(r) : "v"(lo), "v"(hi)); return r; }
; __device__ __forceinline__ void phase_norm(const Params& p, int l, int which, int bid, int G, int tid) {
;     ...
;         for (int i = 0; i < 8; ++i) { const int col = i * 256 + lane * 4; const f32x4 g4 = gnr[i];
;             { const f32x4 sh = *(const f32x4*)(mb + col), sc = *(const f32x4*)(mb + 2048 + col);
;                 const f32x4 o = v[i] * rs * g4 * (sc + 1.f) + sh; u32x2 w; w.x = pk2(o[0], o[1]); w.y = pk2(o[2], o[3]); *(u32x2*)(act + (size_t)row * D + col) = w; }
;             { const f32x4 sh = *(const f32x4*)(mb2 + col), sc = *(const f32x4*)(mb2 + 2048 + col);
;                 const f32x4 o = v2[i] * rs2 * g4 * (sc + 1.f) + sh; u32x2 w; w.x = pk2(o[0], o[1]); w.y = pk2(o[2], o[3]); *(u32x2*)(act + (size_t)row2 * D + col) = w; } }
;     }
	v_pk_add_f32 v[208:209], v[208:209], 1.0 op_sel_hi:[1,0]
	v_pk_add_f32 v[210:211], v[210:211], 1.0 op_sel_hi:[1,0]
	v_pk_fma_f32 v[74:75], v[74:75], v[208:209], v[220:221]
	v_pk_fma_f32 v[76:77], v[76:77], v[210:211], v[222:223]
	v_cvt_pk_bf16_f32 v74, v74, v75
	v_cvt_pk_bf16_f32 v75, v76, v77
	global_store_dwordx2 v[108:109], v[74:75], off offset:-512
	v_lshl_add_u64 v[208:209], v[130:131], 0, v[124:125]
	v_lshl_add_u64 v[220:221], v[128:129], 0, v[124:125]
	global_load_dwordx4 v[208:211], v[208:209], off
	global_load_dwordx4 v[220:223], v[220:221], off
	s_waitcnt vmcnt(19)
	v_pk_add_f32 v[224:225], v[224:225], 1.0 op_sel_hi:[1,0]
	v_pk_add_f32 v[226:227], v[226:227], 1.0 op_sel_hi:[1,0]
	v_pk_fma_f32 v[66:67], v[66:67], v[224:225], v[228:229]
	v_pk_fma_f32 v[68:69], v[68:69], v[226:227], v[230:231]
	v_cvt_pk_bf16_f32 v66, v66, v67
	v_cvt_pk_bf16_f32 v67, v68, v69
	global_store_dwordx2 v[90:91], v[66:67], off offset:1536
	v_lshl_add_u64 v[224:225], v[132:133], 0, v[124:125]
	v_lshl_add_u64 v[228:229], v[94:95], 0, v[124:125]
	global_load_dwordx4 v[224:227], v[224:225], off
	global_load_dwordx4 v[228:231], v[228:229], off
	s_waitcnt vmcnt(20)
	v_pk_add_f32 v[232:233], v[232:233], 1.0 op_sel_hi:[1,0]
	v_pk_add_f32 v[234:235], v[234:235], 1.0 op_sel_hi:[1,0]
	v_pk_fma_f32 v[62:63], v[62:63], v[232:233], v[236:237]
	v_pk_fma_f32 v[64:65], v[64:65], v[234:235], v[238:239]
	v_cvt_pk_bf16_f32 v62, v62, v63
	v_cvt_pk_bf16_f32 v63, v64, v65
	global_store_dwordx2 v[108:109], v[62:63], off
	s_waitcnt vmcnt(19)
	v_pk_add_f32 v[240:241], v[240:241], 1.0 op_sel_hi:[1,0]
	v_pk_add_f32 v[242:243], v[242:243], 1.0 op_sel_hi:[1,0]
	v_pk_fma_f32 v[58:59], v[58:59], v[240:241], v[244:245]
	v_pk_fma_f32 v[60:61], v[60:61], v[242:243], v[246:247]
	v_cvt_pk_bf16_f32 v58, v58, v59
	v_cvt_pk_bf16_f32 v59, v60, v61
	global_store_dwordx2 v[90:91], v[58:59], off offset:2048
	s_waitcnt vmcnt(17)
	v_pk_add_f32 v[156:157], v[156:157], 1.0 op_sel_hi:[1,0]
	v_pk_add_f32 v[158:159], v[158:159], 1.0 op_sel_hi:[1,0]
	v_pk_fma_f32 v[54:55], v[54:55], v[156:157], v[160:161]
	v_pk_fma_f32 v[56:57], v[56:57], v[158:159], v[162:163]
	v_cvt_pk_bf16_f32 v54, v54, v55
	v_cvt_pk_bf16_f32 v55, v56, v57
	global_store_dwordx2 v[108:109], v[54:55], off offset:512
	s_waitcnt vmcnt(15)
	v_pk_add_f32 v[164:165], v[164:165], 1.0 op_sel_hi:[1,0]
	v_pk_add_f32 v[166:167], v[166:167], 1.0 op_sel_hi:[1,0]
	v_pk_fma_f32 v[50:51], v[50:51], v[164:165], v[168:169]
	v_pk_fma_f32 v[52:53], v[52:53], v[166:167], v[170:171]
	v_cvt_pk_bf16_f32 v50, v50, v51
	v_cvt_pk_bf16_f32 v51, v52, v53
	global_store_dwordx2 v[90:91], v[50:51], off offset:2560
	s_waitcnt vmcnt(13)
	v_pk_add_f32 v[172:173], v[172:173], 1.0 op_sel_hi:[1,0]
	v_pk_add_f32 v[174:175], v[174:175], 1.0 op_sel_hi:[1,0]
	v_pk_fma_f32 v[46:47], v[46:47], v[172:173], v[196:197]
	v_pk_fma_f32 v[48:49], v[48:49], v[174:175], v[198:199]
	v_cvt_pk_bf16_f32 v46, v46, v47
	v_cvt_pk_bf16_f32 v47, v48, v49
	global_store_dwordx2 v[108:109], v[46:47], off offset:1024
	s_waitcnt vmcnt(11)
	v_pk_add_f32 v[200:201], v[200:201], 1.0 op_sel_hi:[1,0]
	v_pk_add_f32 v[202:203], v[202:203], 1.0 op_sel_hi:[1,0]
	v_pk_fma_f32 v[42:43], v[42:43], v[200:201], v[204:205]
	v_pk_fma_f32 v[44:45], v[44:45], v[202:203], v[206:207]
	v_cvt_pk_bf16_f32 v42, v42, v43
	v_cvt_pk_bf16_f32 v43, v44, v45
	global_store_dwordx2 v[90:91], v[42:43], off offset:3072
	s_waitcnt vmcnt(9)
	v_pk_add_f32 v[208:209], v[208:209], 1.0 op_sel_hi:[1,0]
	v_pk_add_f32 v[210:211], v[210:211], 1.0 op_sel_hi:[1,0]
	v_pk_fma_f32 v[38:39], v[38:39], v[208:209], v[220:221]
	v_pk_fma_f32 v[40:41], v[40:41], v[210:211], v[222:223]
	v_cvt_pk_bf16_f32 v38, v38, v39
	v_cvt_pk_bf16_f32 v39, v40, v41
	global_store_dwordx2 v[108:109], v[38:39], off offset:1536
	s_waitcnt vmcnt(7)
	v_pk_add_f32 v[224:225], v[224:225], 1.0 op_sel_hi:[1,0]
	v_pk_add_f32 v[226:227], v[226:227], 1.0 op_sel_hi:[1,0]
	v_pk_fma_f32 v[34:35], v[34:35], v[224:225], v[228:229]
	v_pk_fma_f32 v[36:37], v[36:37], v[226:227], v[230:231]
	v_cvt_pk_bf16_f32 v34, v34, v35
	v_cvt_pk_bf16_f32 v35, v36, v37
	global_store_dwordx2 v[90:91], v[34:35], off offset:3584
	v_lshl_add_u64 v[108:109], v[108:109], 0, s[8:9]
	v_add_u32_e32 v46, s14, v102
	v_cmp_lt_i32_e32 vcc, s46, v46
	s_or_b64 s[10:11], vcc, s[10:11]
	s_andn2_b64 exec, exec, s[10:11]
	s_cbranch_execz .LBB0_408
